# G1 rot/plain epilogue stores at agent scope (sc1): written through the XCD L2 instead of staying dirty in it until evicted by the next round
# baseline (speedup 1.0000x reference)
; __device__ __forceinline__ unsigned cvt_pk_bf16(float lo, float hi) { unsigned r; asm volatile("v_cvt_pk_bf16_f32 %0, %1, %2" : "=v"(r) : "v"(lo), "v"(hi)); return r; }
;     __device__ __forceinline__ void operator()(AccT& acc, const Unit& u, int wr, int wc, int fr, int fq) const {
;     ...
;         const int row0 = u.pm * 256 + wr * 64 + fr, col0 = u.pn * 256 + wc * 32 + 8 * fq;
;         const bool rot = u.pn < 4, mqk = (u.pn >= 8 && u.pn < 12);
;         const int i0 = 16 * wc + 4 * fq;
;         if (mqk) {
;             const int mc0 = col0 - 2048;
; #pragma unroll
;             for (int ai = 0; ai < 2; ++ai) { const int grp = u.pm * 4 + ai * 2 + wr;
; #pragma unroll
;                 for (int bj = 0; bj < 2; ++bj) { const int mc = mc0 + bj * 128; const float mul = mc < 512 ? 0.08838834764831845f : 1.0f;
; #pragma unroll
;                     for (int n = 0; n < 2; ++n) {
;                         const f32x4 w0 = *(const f32x4*)(cw + mc + 4 * n), w1 = *(const f32x4*)(cw + 1024 + mc + 4 * n), w2 = *(const f32x4*)(cw + 2048 + mc + 4 * n), b = *(const f32x4*)(cb + mc + 4 * n);
; #pragma unroll
;                         for (int m = 0; m < 4; ++m) { const int lr = m * 16 + fr; const f32x4 gc = acc[ai][bj][m][n]; f32x4 o;
; #pragma unroll
;                             for (int j = 0; j < 4; ++j) { const float gp = dppf_prev(gc[j], m > 0 ? acc[ai][bj][m - 1][n][j] : 0.f), gn = dppf_next(gc[j], m < 3 ? acc[ai][bj][m + 1][n][j] : 0.f);
;                                 const float uu = gp * w0[j] + gc[j] * w1[j] + gn * w2[j] + b[j]; o[j] = uu * sigmoidf_(uu) * mul; }
;                             u32x2 w; w.x = cvt_pk_bf16(o[0], o[1]); w.y = cvt_pk_bf16(o[2], o[3]);
;                             *(u32x2*)(O + (size_t)(grp * 64 + lr) * NPROJ + col0 + bj * 128 + 4 * n) = w;
;                             if (m == 0 || m == 3) { if (lr < 2 || lr > 61) { u32x2 wg; wg.x = cvt_pk_bf16(gc[0], gc[1]); wg.y = cvt_pk_bf16(gc[2], gc[3]);
;                                 *(u32x2*)(HQ + (size_t)(grp * 4 + (lr < 2 ? lr : lr - 60)) * 1024 + mc + 4 * n) = wg; } } } } } }
;             return; }
; #pragma unroll
;         for (int ai = 0; ai < 2; ++ai)
; #pragma unroll
;             for (int m = 0; m < 4; ++m) { const int row = row0 + ai * 128 + m * 16; bf16_t* rowp = O + (size_t)row * NPROJ + col0;
;                 f32x4 cs0 = (f32x4){1.f, 0.f, 1.f, 0.f}, cs1 = cs0;
.LBB0_614:
	s_lshl_b32 s2, s24, 8
	v_mov_b32_e32 v190, v169
	v_mov_b32_e32 v0, v187
	s_or_b32 s2, s2, s52
	s_nop 0
	v_lshl_add_u32 v158, v0, 3, s2
	s_and_b32 s2, s24, -4
	s_cmp_eq_u32 s2, 8
	s_mov_b64 s[2:3], -1
	s_cbranch_scc1 .LBB0_680
	s_lshl_b32 s2, s0, 8
	s_add_i32 s2, s2, s38
	v_add_u32_e32 v140, s2, v190
	v_ashrrev_i32_e32 v159, 31, v158
	v_ashrrev_i32_e32 v141, 31, v140
	v_lshlrev_b64 v[142:143], 13, v[140:141]
	v_lshl_add_u64 v[142:143], s[22:23], 0, v[142:143]
	v_lshl_add_u64 v[142:143], v[158:159], 1, v[142:143]
	s_mov_b32 s2, 0x20000
	s_mov_b32 s3, 0
	s_cmp_lt_i32 s24, 4
	s_cbranch_scc1 .Lg1_rot
	v_cvt_pk_bf16_f32 v164, v126, v127
	v_cvt_pk_bf16_f32 v165, v128, v129
	v_cvt_pk_bf16_f32 v166, v110, v111
	v_cvt_pk_bf16_f32 v167, v112, v113
	global_store_dwordx4 v[142:143], v[164:167], off sc1
	v_cvt_pk_bf16_f32 v178, v94, v95
	v_cvt_pk_bf16_f32 v179, v96, v97
	v_cvt_pk_bf16_f32 v180, v78, v79
	v_cvt_pk_bf16_f32 v181, v80, v81
	global_store_dwordx4 v[142:143], v[178:181], off offset:256 sc1
	v_lshl_add_u64 v[144:145], v[142:143], 0, s[2:3]
	v_cvt_pk_bf16_f32 v164, v122, v123
	v_cvt_pk_bf16_f32 v165, v124, v125
	v_cvt_pk_bf16_f32 v166, v106, v107
	v_cvt_pk_bf16_f32 v167, v108, v109
	global_store_dwordx4 v[144:145], v[164:167], off sc1
	v_cvt_pk_bf16_f32 v178, v90, v91
	v_cvt_pk_bf16_f32 v179, v92, v93
	v_cvt_pk_bf16_f32 v180, v74, v75
	v_cvt_pk_bf16_f32 v181, v76, v77
	global_store_dwordx4 v[144:145], v[178:181], off offset:256 sc1
	v_lshl_add_u64 v[142:143], v[144:145], 0, s[2:3]
	v_cvt_pk_bf16_f32 v164, v118, v119
	v_cvt_pk_bf16_f32 v165, v120, v121
	v_cvt_pk_bf16_f32 v166, v102, v103
	v_cvt_pk_bf16_f32 v167, v104, v105
	global_store_dwordx4 v[142:143], v[164:167], off sc1
	v_cvt_pk_bf16_f32 v178, v86, v87
	v_cvt_pk_bf16_f32 v179, v88, v89
	v_cvt_pk_bf16_f32 v180, v70, v71
	v_cvt_pk_bf16_f32 v181, v72, v73
	global_store_dwordx4 v[142:143], v[178:181], off offset:256 sc1
	v_lshl_add_u64 v[144:145], v[142:143], 0, s[2:3]
	v_cvt_pk_bf16_f32 v164, v114, v115
	v_cvt_pk_bf16_f32 v165, v116, v117
	v_cvt_pk_bf16_f32 v166, v98, v99
	v_cvt_pk_bf16_f32 v167, v100, v101
	global_store_dwordx4 v[144:145], v[164:167], off sc1
	v_cvt_pk_bf16_f32 v178, v82, v83
	v_cvt_pk_bf16_f32 v179, v84, v85
	v_cvt_pk_bf16_f32 v180, v66, v67
	v_cvt_pk_bf16_f32 v181, v68, v69
	global_store_dwordx4 v[144:145], v[178:181], off offset:256 sc1
	v_lshl_add_u64 v[142:143], v[144:145], 0, s[2:3]
	v_lshl_add_u64 v[142:143], v[142:143], 0, s[2:3]
	v_lshl_add_u64 v[142:143], v[142:143], 0, s[2:3]
	v_lshl_add_u64 v[142:143], v[142:143], 0, s[2:3]
	v_lshl_add_u64 v[142:143], v[142:143], 0, s[2:3]
	v_cvt_pk_bf16_f32 v164, v62, v63
	v_cvt_pk_bf16_f32 v165, v64, v65
	v_cvt_pk_bf16_f32 v166, v46, v47
	v_cvt_pk_bf16_f32 v167, v48, v49
	global_store_dwordx4 v[142:143], v[164:167], off sc1
	v_cvt_pk_bf16_f32 v178, v30, v31
	v_cvt_pk_bf16_f32 v179, v32, v33
	v_cvt_pk_bf16_f32 v180, v14, v15
	v_cvt_pk_bf16_f32 v181, v16, v17
	global_store_dwordx4 v[142:143], v[178:181], off offset:256 sc1
	v_lshl_add_u64 v[144:145], v[142:143], 0, s[2:3]
	v_cvt_pk_bf16_f32 v164, v58, v59
	v_cvt_pk_bf16_f32 v165, v60, v61
	v_cvt_pk_bf16_f32 v166, v42, v43
	v_cvt_pk_bf16_f32 v167, v44, v45
	global_store_dwordx4 v[144:145], v[164:167], off sc1
	v_cvt_pk_bf16_f32 v178, v26, v27
	v_cvt_pk_bf16_f32 v179, v28, v29
	v_cvt_pk_bf16_f32 v180, v10, v11
	v_cvt_pk_bf16_f32 v181, v12, v13
	global_store_dwordx4 v[144:145], v[178:181], off offset:256 sc1
	v_lshl_add_u64 v[142:143], v[144:145], 0, s[2:3]
	v_cvt_pk_bf16_f32 v164, v54, v55
	v_cvt_pk_bf16_f32 v165, v56, v57
	v_cvt_pk_bf16_f32 v166, v38, v39
	v_cvt_pk_bf16_f32 v167, v40, v41
	global_store_dwordx4 v[142:143], v[164:167], off sc1
	v_cvt_pk_bf16_f32 v178, v22, v23
	v_cvt_pk_bf16_f32 v179, v24, v25
	v_cvt_pk_bf16_f32 v180, v6, v7
	v_cvt_pk_bf16_f32 v181, v8, v9
	global_store_dwordx4 v[142:143], v[178:181], off offset:256 sc1
	v_lshl_add_u64 v[144:145], v[142:143], 0, s[2:3]
	v_cvt_pk_bf16_f32 v164, v50, v51
	v_cvt_pk_bf16_f32 v165, v52, v53
	v_cvt_pk_bf16_f32 v166, v34, v35
	v_cvt_pk_bf16_f32 v167, v36, v37
	global_store_dwordx4 v[144:145], v[164:167], off sc1
	v_cvt_pk_bf16_f32 v178, v18, v19
	v_cvt_pk_bf16_f32 v179, v20, v21
	v_cvt_pk_bf16_f32 v180, v2, v3
	v_cvt_pk_bf16_f32 v181, v4, v5
	global_store_dwordx4 v[144:145], v[178:181], off offset:256 sc1
	s_branch .Lg1_epi_done
;     __device__ __forceinline__ void operator()(AccT& acc, const Unit& u, int wr, int wc, int fr, int fq) const {
;     ...
;             for (int m = 0; m < 4; ++m) { const int row = row0 + ai * 128 + m * 16; bf16_t* rowp = O + (size_t)row * NPROJ + col0;
;                 f32x4 cs0 = (f32x4){1.f, 0.f, 1.f, 0.f}, cs1 = cs0;
;                 if (rot) { const int pos = row < HALF_TOK ? (row & 8191) : ((row - HALF_TOK) & 2047); const f32x2* rp = rope + (size_t)pos * 64 + i0; cs0 = *(const f32x4*)rp; cs1 = *(const f32x4*)(rp + 2); }
; #pragma unroll
;                 for (int bj = 0; bj < 2; ++bj) { f32x4 v0 = acc[ai][bj][m][0], v1 = acc[ai][bj][m][1];
;                     if (rot) { const f32x4 a = v0, b = v1;
;                         v0[0] = a[0] * cs0[0] - a[1] * cs0[1]; v0[1] = a[1] * cs0[0] + a[0] * cs0[1]; v0[2] = a[2] * cs0[2] - a[3] * cs0[3]; v0[3] = a[3] * cs0[2] + a[2] * cs0[3];
;                         v1[0] = b[0] * cs1[0] - b[1] * cs1[1]; v1[1] = b[1] * cs1[0] + b[0] * cs1[1]; v1[2] = b[2] * cs1[2] - b[3] * cs1[3]; v1[3] = b[3] * cs1[2] + b[2] * cs1[3]; }
.Lg1_rot:
	s_movk_i32 s4, 0x4000
	v_lshl_add_u32 v138, v0, 2, s79
	v_cmp_gt_i32_e32 vcc, s4, v140
	v_mov_b32_e32 v0, 0x7ff
	v_mov_b32_e32 v160, 0x1fff
	v_ashrrev_i32_e32 v139, 31, v138
	v_cndmask_b32_e32 v0, v0, v160, vcc
	v_and_b32_e32 v0, v0, v140
	v_lshlrev_b32_e32 v0, 9, v0
	v_lshl_add_u64 v[160:161], s[46:47], 0, v[0:1]
	v_lshl_add_u64 v[138:139], v[138:139], 3, v[160:161]
	s_mov_b32 s42, 0x2000
	s_mov_b32 s43, 0
	global_load_dwordx4 v[134:137], v[138:139], off
	global_load_dwordx4 v[130:133], v[138:139], off offset:16
	s_nop 0
	v_lshl_add_u64 v[138:139], v[138:139], 0, s[42:43]
	global_load_dwordx4 v[182:185], v[138:139], off
	global_load_dwordx4 v[192:195], v[138:139], off offset:16
	s_nop 0
	v_lshl_add_u64 v[138:139], v[138:139], 0, s[42:43]
	global_load_dwordx4 v[196:199], v[138:139], off
	global_load_dwordx4 v[204:207], v[138:139], off offset:16
	s_nop 0
	v_lshl_add_u64 v[138:139], v[138:139], 0, s[42:43]
	global_load_dwordx4 v[222:225], v[138:139], off
	global_load_dwordx4 v[226:229], v[138:139], off offset:16
	s_nop 0
	v_lshl_add_u64 v[138:139], v[138:139], 0, s[42:43]
	v_lshl_add_u64 v[138:139], v[138:139], 0, s[42:43]
	v_lshl_add_u64 v[138:139], v[138:139], 0, s[42:43]
	v_lshl_add_u64 v[138:139], v[138:139], 0, s[42:43]
	v_lshl_add_u64 v[138:139], v[138:139], 0, s[42:43]
	s_waitcnt vmcnt(6)
	v_mul_f32_e32 v0, v127, v135
	v_mul_f32_e32 v172, v111, v131
	v_mul_f32_e32 v160, v126, v135
	v_mul_f32_e32 v173, v110, v131
	v_mul_f32_e32 v161, v126, v134
	v_mul_f32_e32 v174, v110, v130
	v_mul_f32_e32 v170, v137, v129
	v_mul_f32_e32 v175, v133, v113
	v_mul_f32_e32 v171, v128, v137
	v_mul_f32_e32 v176, v112, v133
	v_fma_f32 v127, v127, v134, v160
	v_fma_f32 v111, v111, v130, v173
	v_sub_f32_e32 v126, v161, v0
	v_sub_f32_e32 v110, v174, v172
	v_fma_f32 v128, v136, v128, -v170
	v_fma_f32 v112, v132, v112, -v175
	v_fma_f32 v129, v129, v136, v171
	v_fma_f32 v113, v113, v132, v176
	v_mul_f32_e32 v0, v95, v135
	v_mul_f32_e32 v172, v79, v131
	v_mul_f32_e32 v160, v94, v135
	v_mul_f32_e32 v173, v78, v131
	v_mul_f32_e32 v161, v94, v134
	v_mul_f32_e32 v174, v78, v130
	v_mul_f32_e32 v170, v137, v97
	v_mul_f32_e32 v175, v133, v81
	v_mul_f32_e32 v171, v96, v137
	v_mul_f32_e32 v176, v80, v133
	v_fma_f32 v95, v95, v134, v160
	v_fma_f32 v79, v79, v130, v173
	v_sub_f32_e32 v94, v161, v0
	v_sub_f32_e32 v78, v174, v172
	v_fma_f32 v96, v136, v96, -v170
	v_fma_f32 v80, v132, v80, -v175
	v_fma_f32 v97, v97, v136, v171
	v_fma_f32 v81, v81, v132, v176
	global_load_dwordx4 v[134:137], v[138:139], off
	global_load_dwordx4 v[130:133], v[138:139], off offset:16
	s_nop 0
	v_lshl_add_u64 v[138:139], v[138:139], 0, s[42:43]
	s_waitcnt vmcnt(6)
	v_mul_f32_e32 v0, v123, v183
	v_mul_f32_e32 v172, v107, v193
	v_mul_f32_e32 v160, v122, v183
	v_mul_f32_e32 v173, v106, v193
	v_mul_f32_e32 v161, v122, v182
	v_mul_f32_e32 v174, v106, v192
	v_mul_f32_e32 v170, v185, v125
	v_mul_f32_e32 v175, v195, v109
	v_mul_f32_e32 v171, v124, v185
	v_mul_f32_e32 v176, v108, v195
	v_fma_f32 v123, v123, v182, v160
	v_fma_f32 v107, v107, v192, v173
	v_sub_f32_e32 v122, v161, v0
	v_sub_f32_e32 v106, v174, v172
	v_fma_f32 v124, v184, v124, -v170
	v_fma_f32 v108, v194, v108, -v175
	v_fma_f32 v125, v125, v184, v171
	v_fma_f32 v109, v109, v194, v176
	v_mul_f32_e32 v0, v91, v183
	v_mul_f32_e32 v172, v75, v193
	v_mul_f32_e32 v160, v90, v183
	v_mul_f32_e32 v173, v74, v193
	v_mul_f32_e32 v161, v90, v182
	v_mul_f32_e32 v174, v74, v192
	v_mul_f32_e32 v170, v185, v93
	v_mul_f32_e32 v175, v195, v77
	v_mul_f32_e32 v171, v92, v185
	v_mul_f32_e32 v176, v76, v195
	v_fma_f32 v91, v91, v182, v160
	v_fma_f32 v75, v75, v192, v173
	v_sub_f32_e32 v90, v161, v0
	v_sub_f32_e32 v74, v174, v172
	v_fma_f32 v92, v184, v92, -v170
	v_fma_f32 v76, v194, v76, -v175
	v_fma_f32 v93, v93, v184, v171
	v_fma_f32 v77, v77, v194, v176
	global_load_dwordx4 v[182:185], v[138:139], off
	global_load_dwordx4 v[192:195], v[138:139], off offset:16
	s_nop 0
	v_lshl_add_u64 v[138:139], v[138:139], 0, s[42:43]
	s_waitcnt vmcnt(6)
	v_mul_f32_e32 v0, v119, v197
	v_mul_f32_e32 v172, v103, v205
	v_mul_f32_e32 v160, v118, v197
	v_mul_f32_e32 v173, v102, v205
	v_mul_f32_e32 v161, v118, v196
	v_mul_f32_e32 v174, v102, v204
	v_mul_f32_e32 v170, v199, v121
	v_mul_f32_e32 v175, v207, v105
	v_mul_f32_e32 v171, v120, v199
	v_mul_f32_e32 v176, v104, v207
	v_fma_f32 v119, v119, v196, v160
	v_fma_f32 v103, v103, v204, v173
	v_sub_f32_e32 v118, v161, v0
	v_sub_f32_e32 v102, v174, v172
	v_fma_f32 v120, v198, v120, -v170
	v_fma_f32 v104, v206, v104, -v175
	v_fma_f32 v121, v121, v198, v171
	v_fma_f32 v105, v105, v206, v176
	v_mul_f32_e32 v0, v87, v197
	v_mul_f32_e32 v172, v71, v205
	v_mul_f32_e32 v160, v86, v197
	v_mul_f32_e32 v173, v70, v205
	v_mul_f32_e32 v161, v86, v196
	v_mul_f32_e32 v174, v70, v204
	v_mul_f32_e32 v170, v199, v89
	v_mul_f32_e32 v175, v207, v73
	v_mul_f32_e32 v171, v88, v199
	v_mul_f32_e32 v176, v72, v207
	v_fma_f32 v87, v87, v196, v160
	v_fma_f32 v71, v71, v204, v173
	v_sub_f32_e32 v86, v161, v0
	v_sub_f32_e32 v70, v174, v172
	v_fma_f32 v88, v198, v88, -v170
	v_fma_f32 v72, v206, v72, -v175
	v_fma_f32 v89, v89, v198, v171
	v_fma_f32 v73, v73, v206, v176
	global_load_dwordx4 v[196:199], v[138:139], off
	global_load_dwordx4 v[204:207], v[138:139], off offset:16
	s_nop 0
	v_lshl_add_u64 v[138:139], v[138:139], 0, s[42:43]
	s_waitcnt vmcnt(6)
;     __device__ __forceinline__ void operator()(AccT& acc, const Unit& u, int wr, int wc, int fr, int fq) const {
;     ...
;                 for (int bj = 0; bj < 2; ++bj) { f32x4 v0 = acc[ai][bj][m][0], v1 = acc[ai][bj][m][1];
;                     if (rot) { const f32x4 a = v0, b = v1;
;                         v0[0] = a[0] * cs0[0] - a[1] * cs0[1]; v0[1] = a[1] * cs0[0] + a[0] * cs0[1]; v0[2] = a[2] * cs0[2] - a[3] * cs0[3]; v0[3] = a[3] * cs0[2] + a[2] * cs0[3];
;                         v1[0] = b[0] * cs1[0] - b[1] * cs1[1]; v1[1] = b[1] * cs1[0] + b[0] * cs1[1]; v1[2] = b[2] * cs1[2] - b[3] * cs1[3]; v1[3] = b[3] * cs1[2] + b[2] * cs1[3]; }
	v_mul_f32_e32 v0, v115, v223
	v_mul_f32_e32 v172, v99, v227
	v_mul_f32_e32 v160, v114, v223
	v_mul_f32_e32 v173, v98, v227
	v_mul_f32_e32 v161, v114, v222
	v_mul_f32_e32 v174, v98, v226
	v_mul_f32_e32 v170, v225, v117
	v_mul_f32_e32 v175, v229, v101
	v_mul_f32_e32 v171, v116, v225
	v_mul_f32_e32 v176, v100, v229
	v_fma_f32 v115, v115, v222, v160
	v_fma_f32 v99, v99, v226, v173
	v_sub_f32_e32 v114, v161, v0
	v_sub_f32_e32 v98, v174, v172
	v_fma_f32 v116, v224, v116, -v170
	v_fma_f32 v100, v228, v100, -v175
	v_fma_f32 v117, v117, v224, v171
	v_fma_f32 v101, v101, v228, v176
	v_mul_f32_e32 v0, v83, v223
	v_mul_f32_e32 v172, v67, v227
	v_mul_f32_e32 v160, v82, v223
	v_mul_f32_e32 v173, v66, v227
	v_mul_f32_e32 v161, v82, v222
	v_mul_f32_e32 v174, v66, v226
	v_mul_f32_e32 v170, v225, v85
	v_mul_f32_e32 v175, v229, v69
	v_mul_f32_e32 v171, v84, v225
	v_mul_f32_e32 v176, v68, v229
	v_fma_f32 v83, v83, v222, v160
	v_fma_f32 v67, v67, v226, v173
	v_sub_f32_e32 v82, v161, v0
	v_sub_f32_e32 v66, v174, v172
	v_fma_f32 v84, v224, v84, -v170
	v_fma_f32 v68, v228, v68, -v175
	v_fma_f32 v85, v85, v224, v171
	v_fma_f32 v69, v69, v228, v176
	global_load_dwordx4 v[222:225], v[138:139], off
	global_load_dwordx4 v[226:229], v[138:139], off offset:16
	s_waitcnt vmcnt(6)
	v_mul_f32_e32 v0, v63, v135
	v_mul_f32_e32 v172, v47, v131
	v_mul_f32_e32 v160, v62, v135
	v_mul_f32_e32 v173, v46, v131
	v_mul_f32_e32 v161, v62, v134
	v_mul_f32_e32 v174, v46, v130
	v_mul_f32_e32 v170, v137, v65
	v_mul_f32_e32 v175, v133, v49
	v_mul_f32_e32 v171, v64, v137
	v_mul_f32_e32 v176, v48, v133
	v_fma_f32 v63, v63, v134, v160
	v_fma_f32 v47, v47, v130, v173
	v_sub_f32_e32 v62, v161, v0
	v_sub_f32_e32 v46, v174, v172
	v_fma_f32 v64, v136, v64, -v170
	v_fma_f32 v48, v132, v48, -v175
	v_fma_f32 v65, v65, v136, v171
	v_fma_f32 v49, v49, v132, v176
	v_mul_f32_e32 v0, v31, v135
	v_mul_f32_e32 v172, v15, v131
	v_mul_f32_e32 v160, v30, v135
	v_mul_f32_e32 v173, v14, v131
	v_mul_f32_e32 v161, v30, v134
	v_mul_f32_e32 v174, v14, v130
	v_mul_f32_e32 v170, v137, v33
	v_mul_f32_e32 v175, v133, v17
	v_mul_f32_e32 v171, v32, v137
	v_mul_f32_e32 v176, v16, v133
	v_fma_f32 v31, v31, v134, v160
	v_fma_f32 v15, v15, v130, v173
	v_sub_f32_e32 v30, v161, v0
	v_sub_f32_e32 v14, v174, v172
	v_fma_f32 v32, v136, v32, -v170
	v_fma_f32 v16, v132, v16, -v175
	v_fma_f32 v33, v33, v136, v171
	v_fma_f32 v17, v17, v132, v176
	s_waitcnt vmcnt(4)
	v_mul_f32_e32 v0, v59, v183
	v_mul_f32_e32 v172, v43, v193
	v_mul_f32_e32 v160, v58, v183
	v_mul_f32_e32 v173, v42, v193
	v_mul_f32_e32 v161, v58, v182
	v_mul_f32_e32 v174, v42, v192
	v_mul_f32_e32 v170, v185, v61
	v_mul_f32_e32 v175, v195, v45
	v_mul_f32_e32 v171, v60, v185
	v_mul_f32_e32 v176, v44, v195
	v_fma_f32 v59, v59, v182, v160
	v_fma_f32 v43, v43, v192, v173
	v_sub_f32_e32 v58, v161, v0
	v_sub_f32_e32 v42, v174, v172
	v_fma_f32 v60, v184, v60, -v170
	v_fma_f32 v44, v194, v44, -v175
	v_fma_f32 v61, v61, v184, v171
	v_fma_f32 v45, v45, v194, v176
	v_mul_f32_e32 v0, v27, v183
	v_mul_f32_e32 v172, v11, v193
	v_mul_f32_e32 v160, v26, v183
	v_mul_f32_e32 v173, v10, v193
	v_mul_f32_e32 v161, v26, v182
	v_mul_f32_e32 v174, v10, v192
	v_mul_f32_e32 v170, v185, v29
	v_mul_f32_e32 v175, v195, v13
	v_mul_f32_e32 v171, v28, v185
	v_mul_f32_e32 v176, v12, v195
	v_fma_f32 v27, v27, v182, v160
	v_fma_f32 v11, v11, v192, v173
	v_sub_f32_e32 v26, v161, v0
	v_sub_f32_e32 v10, v174, v172
	v_fma_f32 v28, v184, v28, -v170
	v_fma_f32 v12, v194, v12, -v175
	v_fma_f32 v29, v29, v184, v171
	v_fma_f32 v13, v13, v194, v176
	s_waitcnt vmcnt(2)
	v_mul_f32_e32 v0, v55, v197
	v_mul_f32_e32 v172, v39, v205
	v_mul_f32_e32 v160, v54, v197
	v_mul_f32_e32 v173, v38, v205
	v_mul_f32_e32 v161, v54, v196
	v_mul_f32_e32 v174, v38, v204
	v_mul_f32_e32 v170, v199, v57
	v_mul_f32_e32 v175, v207, v41
	v_mul_f32_e32 v171, v56, v199
	v_mul_f32_e32 v176, v40, v207
	v_fma_f32 v55, v55, v196, v160
	v_fma_f32 v39, v39, v204, v173
	v_sub_f32_e32 v54, v161, v0
	v_sub_f32_e32 v38, v174, v172
	v_fma_f32 v56, v198, v56, -v170
	v_fma_f32 v40, v206, v40, -v175
	v_fma_f32 v57, v57, v198, v171
	v_fma_f32 v41, v41, v206, v176
	v_mul_f32_e32 v0, v23, v197
	v_mul_f32_e32 v172, v7, v205
	v_mul_f32_e32 v160, v22, v197
	v_mul_f32_e32 v173, v6, v205
	v_mul_f32_e32 v161, v22, v196
	v_mul_f32_e32 v174, v6, v204
	v_mul_f32_e32 v170, v199, v25
	v_mul_f32_e32 v175, v207, v9
	v_mul_f32_e32 v171, v24, v199
	v_mul_f32_e32 v176, v8, v207
	v_fma_f32 v23, v23, v196, v160
	v_fma_f32 v7, v7, v204, v173
	v_sub_f32_e32 v22, v161, v0
	v_sub_f32_e32 v6, v174, v172
	v_fma_f32 v24, v198, v24, -v170
	v_fma_f32 v8, v206, v8, -v175
	v_fma_f32 v25, v25, v198, v171
	v_fma_f32 v9, v9, v206, v176
	s_waitcnt vmcnt(0)
; __device__ __forceinline__ unsigned cvt_pk_bf16(float lo, float hi) { unsigned r; asm volatile("v_cvt_pk_bf16_f32 %0, %1, %2" : "=v"(r) : "v"(lo), "v"(hi)); return r; }
;     __device__ __forceinline__ void operator()(AccT& acc, const Unit& u, int wr, int wc, int fr, int fq) const {
;     ...
;                 for (int bj = 0; bj < 2; ++bj) { f32x4 v0 = acc[ai][bj][m][0], v1 = acc[ai][bj][m][1];
;                     if (rot) { const f32x4 a = v0, b = v1;
;                         v0[0] = a[0] * cs0[0] - a[1] * cs0[1]; v0[1] = a[1] * cs0[0] + a[0] * cs0[1]; v0[2] = a[2] * cs0[2] - a[3] * cs0[3]; v0[3] = a[3] * cs0[2] + a[2] * cs0[3];
;                         v1[0] = b[0] * cs1[0] - b[1] * cs1[1]; v1[1] = b[1] * cs1[0] + b[0] * cs1[1]; v1[2] = b[2] * cs1[2] - b[3] * cs1[3]; v1[3] = b[3] * cs1[2] + b[2] * cs1[3]; }
;                     u32x4 w; w.x = cvt_pk_bf16(v0[0], v0[1]); w.y = cvt_pk_bf16(v0[2], v0[3]); w.z = cvt_pk_bf16(v1[0], v1[1]); w.w = cvt_pk_bf16(v1[2], v1[3]);
;                     *(u32x4*)(rowp + bj * 128) = w; }
	v_mul_f32_e32 v0, v51, v223
	v_mul_f32_e32 v172, v35, v227
	v_mul_f32_e32 v160, v50, v223
	v_mul_f32_e32 v173, v34, v227
	v_mul_f32_e32 v161, v50, v222
	v_mul_f32_e32 v174, v34, v226
	v_mul_f32_e32 v170, v225, v53
	v_mul_f32_e32 v175, v229, v37
	v_mul_f32_e32 v171, v52, v225
	v_mul_f32_e32 v176, v36, v229
	v_fma_f32 v51, v51, v222, v160
	v_fma_f32 v35, v35, v226, v173
	v_sub_f32_e32 v50, v161, v0
	v_sub_f32_e32 v34, v174, v172
	v_fma_f32 v52, v224, v52, -v170
	v_fma_f32 v36, v228, v36, -v175
	v_fma_f32 v53, v53, v224, v171
	v_fma_f32 v37, v37, v228, v176
	v_mul_f32_e32 v0, v19, v223
	v_mul_f32_e32 v172, v3, v227
	v_mul_f32_e32 v160, v18, v223
	v_mul_f32_e32 v173, v2, v227
	v_mul_f32_e32 v161, v18, v222
	v_mul_f32_e32 v174, v2, v226
	v_mul_f32_e32 v170, v225, v21
	v_mul_f32_e32 v175, v229, v5
	v_mul_f32_e32 v171, v20, v225
	v_mul_f32_e32 v176, v4, v229
	v_fma_f32 v19, v19, v222, v160
	v_fma_f32 v3, v3, v226, v173
	v_sub_f32_e32 v18, v161, v0
	v_sub_f32_e32 v2, v174, v172
	v_fma_f32 v20, v224, v20, -v170
	v_fma_f32 v4, v228, v4, -v175
	v_fma_f32 v21, v21, v224, v171
	v_fma_f32 v5, v5, v228, v176
	v_cvt_pk_bf16_f32 v164, v126, v127
	v_cvt_pk_bf16_f32 v165, v128, v129
	v_cvt_pk_bf16_f32 v166, v110, v111
	v_cvt_pk_bf16_f32 v167, v112, v113
	global_store_dwordx4 v[142:143], v[164:167], off sc1
	v_cvt_pk_bf16_f32 v178, v94, v95
	v_cvt_pk_bf16_f32 v179, v96, v97
	v_cvt_pk_bf16_f32 v180, v78, v79
	v_cvt_pk_bf16_f32 v181, v80, v81
	global_store_dwordx4 v[142:143], v[178:181], off offset:256 sc1
	v_lshl_add_u64 v[144:145], v[142:143], 0, s[2:3]
	v_cvt_pk_bf16_f32 v164, v122, v123
	v_cvt_pk_bf16_f32 v165, v124, v125
	v_cvt_pk_bf16_f32 v166, v106, v107
	v_cvt_pk_bf16_f32 v167, v108, v109
	global_store_dwordx4 v[144:145], v[164:167], off sc1
	v_cvt_pk_bf16_f32 v178, v90, v91
	v_cvt_pk_bf16_f32 v179, v92, v93
	v_cvt_pk_bf16_f32 v180, v74, v75
	v_cvt_pk_bf16_f32 v181, v76, v77
	global_store_dwordx4 v[144:145], v[178:181], off offset:256 sc1
	v_lshl_add_u64 v[142:143], v[144:145], 0, s[2:3]
	v_cvt_pk_bf16_f32 v164, v118, v119
	v_cvt_pk_bf16_f32 v165, v120, v121
	v_cvt_pk_bf16_f32 v166, v102, v103
	v_cvt_pk_bf16_f32 v167, v104, v105
	global_store_dwordx4 v[142:143], v[164:167], off sc1
	v_cvt_pk_bf16_f32 v178, v86, v87
	v_cvt_pk_bf16_f32 v179, v88, v89
	v_cvt_pk_bf16_f32 v180, v70, v71
	v_cvt_pk_bf16_f32 v181, v72, v73
	global_store_dwordx4 v[142:143], v[178:181], off offset:256 sc1
	v_lshl_add_u64 v[144:145], v[142:143], 0, s[2:3]
	v_cvt_pk_bf16_f32 v164, v114, v115
	v_cvt_pk_bf16_f32 v165, v116, v117
	v_cvt_pk_bf16_f32 v166, v98, v99
	v_cvt_pk_bf16_f32 v167, v100, v101
	global_store_dwordx4 v[144:145], v[164:167], off sc1
	v_cvt_pk_bf16_f32 v178, v82, v83
	v_cvt_pk_bf16_f32 v179, v84, v85
	v_cvt_pk_bf16_f32 v180, v66, v67
	v_cvt_pk_bf16_f32 v181, v68, v69
	global_store_dwordx4 v[144:145], v[178:181], off offset:256 sc1
	v_lshl_add_u64 v[142:143], v[144:145], 0, s[2:3]
	v_lshl_add_u64 v[142:143], v[142:143], 0, s[2:3]
	v_lshl_add_u64 v[142:143], v[142:143], 0, s[2:3]
	v_lshl_add_u64 v[142:143], v[142:143], 0, s[2:3]
	v_lshl_add_u64 v[142:143], v[142:143], 0, s[2:3]
	v_cvt_pk_bf16_f32 v164, v62, v63
	v_cvt_pk_bf16_f32 v165, v64, v65
	v_cvt_pk_bf16_f32 v166, v46, v47
	v_cvt_pk_bf16_f32 v167, v48, v49
	global_store_dwordx4 v[142:143], v[164:167], off sc1
	v_cvt_pk_bf16_f32 v178, v30, v31
	v_cvt_pk_bf16_f32 v179, v32, v33
	v_cvt_pk_bf16_f32 v180, v14, v15
	v_cvt_pk_bf16_f32 v181, v16, v17
	global_store_dwordx4 v[142:143], v[178:181], off offset:256 sc1
	v_lshl_add_u64 v[144:145], v[142:143], 0, s[2:3]
	v_cvt_pk_bf16_f32 v164, v58, v59
	v_cvt_pk_bf16_f32 v165, v60, v61
	v_cvt_pk_bf16_f32 v166, v42, v43
	v_cvt_pk_bf16_f32 v167, v44, v45
	global_store_dwordx4 v[144:145], v[164:167], off sc1
	v_cvt_pk_bf16_f32 v178, v26, v27
	v_cvt_pk_bf16_f32 v179, v28, v29
	v_cvt_pk_bf16_f32 v180, v10, v11
	v_cvt_pk_bf16_f32 v181, v12, v13
	global_store_dwordx4 v[144:145], v[178:181], off offset:256 sc1
	v_lshl_add_u64 v[142:143], v[144:145], 0, s[2:3]
	v_cvt_pk_bf16_f32 v164, v54, v55
	v_cvt_pk_bf16_f32 v165, v56, v57
	v_cvt_pk_bf16_f32 v166, v38, v39
	v_cvt_pk_bf16_f32 v167, v40, v41
	global_store_dwordx4 v[142:143], v[164:167], off sc1
	v_cvt_pk_bf16_f32 v178, v22, v23
	v_cvt_pk_bf16_f32 v179, v24, v25
	v_cvt_pk_bf16_f32 v180, v6, v7
	v_cvt_pk_bf16_f32 v181, v8, v9
	global_store_dwordx4 v[142:143], v[178:181], off offset:256 sc1
	v_lshl_add_u64 v[144:145], v[142:143], 0, s[2:3]
	v_cvt_pk_bf16_f32 v164, v50, v51
	v_cvt_pk_bf16_f32 v165, v52, v53
	v_cvt_pk_bf16_f32 v166, v34, v35
	v_cvt_pk_bf16_f32 v167, v36, v37
	global_store_dwordx4 v[144:145], v[164:167], off sc1
	v_cvt_pk_bf16_f32 v178, v18, v19
	v_cvt_pk_bf16_f32 v179, v20, v21
	v_cvt_pk_bf16_f32 v180, v2, v3
	v_cvt_pk_bf16_f32 v181, v4, v5
	global_store_dwordx4 v[144:145], v[178:181], off offset:256 sc1
